# attention: score arithmetic and x-max subtraction two elements at a time with packed f32 FMA/add (bit-identical), per-item constants in SGPR pairs
# speedup vs baseline: 1.0021x; 1.0021x over previous
.LBB0_229:
	s_or_b64 exec, exec, s[0:1]
	s_waitcnt lgkmcnt(0)
	s_barrier
	ds_read_b32 v0, v181
	s_mov_b64 s[0:1], -1
	s_waitcnt lgkmcnt(0)
	v_cmp_lt_i32_e32 vcc, s25, v0
	v_readfirstlane_b32 s4, v0
	s_cbranch_vccnz .LBB0_224
	s_ashr_i32 s0, s4, 31
	s_lshr_b32 s0, s0, 23
	s_add_i32 s0, s4, s0
	s_and_b32 s0, s0, 0xfffffe00
	s_sub_i32 s6, s4, s0
	v_readfirstlane_b32 s0, v183
	s_ashr_i32 s7, s6, 5
	s_lshr_b32 s0, s0, 2
	s_sub_i32 s8, 15, s7
	s_and_b32 s9, s0, 0x3ffffff0
	s_lshl_b32 s0, s6, 8
	s_and_b32 s4, s6, 7
	s_lshl_b32 s5, s8, 7
	s_and_b32 s16, s0, 0x1800
	s_add_i32 s37, s9, s5
	s_add_i32 s10, s4, 1
	s_mul_i32 s0, s16, 0xc000
	s_add_u32 s0, s74, s0
	s_addc_u32 s1, s75, 0
	s_lshl_b32 s36, s4, 8
	s_mul_i32 s11, s8, 0x600000
	s_mul_hi_u32 s5, s5, 0xc000
	s_add_u32 s11, s0, s11
	s_addc_u32 s5, s1, s5
	s_lshl_b32 s4, s4, 9
	s_add_u32 s4, s11, s4
	s_addc_u32 s5, s5, 0
	v_mov_b32_e32 v149, v145
	v_lshl_add_u64 v[0:1], s[4:5], 0, v[148:149]
	v_lshl_add_u64 v[28:29], v[0:1], 0, s[18:19]
	v_mov_b32_e32 v151, v145
	v_lshl_add_u64 v[24:25], v[28:29], 0, v[150:151]
	v_add_co_u32_e32 v8, vcc, s27, v24
	v_mov_b32_e32 v153, v145
	s_nop 0
	v_addc_co_u32_e32 v9, vcc, 0, v25, vcc
	v_add_co_u32_e32 v16, vcc, s28, v24
	v_or_b32_e32 v33, s36, v174
	s_waitcnt lgkmcnt(0)
	s_barrier
	v_lshl_add_u64 v[4:5], v[28:29], 0, v[152:153]
	v_addc_co_u32_e32 v17, vcc, 0, v25, vcc
	global_load_dwordx4 v[0:3], v[24:25], off
	s_nop 0
	global_load_dwordx4 v[4:7], v[4:5], off
	v_add_co_u32_e32 v24, vcc, s29, v24
	v_lshlrev_b32_e32 v162, 1, v33
	v_mov_b32_e32 v163, v145
	v_or_b32_e32 v32, s36, v173
	v_mov_b32_e32 v155, v145
	v_mov_b32_e32 v157, v145
	v_addc_co_u32_e32 v25, vcc, 0, v25, vcc
	v_mov_b32_e32 v159, v145
	v_lshl_add_u64 v[48:49], s[0:1], 0, v[162:163]
	v_lshl_add_u64 v[12:13], v[28:29], 0, v[154:155]
	v_lshl_add_u64 v[20:21], v[28:29], 0, v[156:157]
	v_lshl_add_u64 v[28:29], v[28:29], 0, v[158:159]
	v_lshlrev_b32_e32 v144, 1, v32
	v_add_co_u32_e32 v44, vcc, s30, v48
	global_load_dwordx4 v[8:11], v[8:9], off
	s_nop 0
	global_load_dwordx4 v[12:15], v[12:13], off
	s_nop 0
	global_load_dwordx4 v[16:19], v[16:17], off
	s_nop 0
	global_load_dwordx4 v[20:23], v[20:21], off
	v_addc_co_u32_e32 v45, vcc, 0, v49, vcc
	global_load_dwordx4 v[24:27], v[24:25], off
	v_lshl_add_u64 v[50:51], s[0:1], 0, v[144:145]
	global_load_dwordx4 v[28:31], v[28:29], off
	s_nop 0
	global_load_dwordx4 v[32:35], v144, s[0:1]
	global_load_dwordx4 v[36:39], v144, s[0:1] offset:256
	s_lshl_b32 s38, s8, 2
	v_add_co_u32_e32 v50, vcc, s27, v50
	s_add_i32 s38, s38, 4
	global_load_dwordx4 v[40:43], v162, s[0:1]
	v_addc_co_u32_e32 v51, vcc, 0, v51, vcc
	global_load_dwordx4 v[44:47], v[44:45], off
	s_add_u32 s0, s0, 0x180000
	v_add_co_u32_e32 v48, vcc, s31, v48
	s_addc_u32 s1, s1, 0
	s_nop 0
	v_addc_co_u32_e32 v49, vcc, 0, v49, vcc
	global_load_dwordx4 v[116:119], v[50:51], off offset:256
	global_load_dwordx4 v[132:135], v[48:49], off
	global_load_dwordx4 v[124:127], v144, s[0:1]
	global_load_dwordx4 v[140:143], v162, s[0:1]
	v_cvt_f32_ubyte0_e32 v48, s10
	s_bfe_u32 s0, s6, 0x20003
	v_exp_f32_e64 v48, -v48
	s_or_b32 s41, s37, 15
	s_mul_i32 s0, s0, 0x6000000
	s_add_u32 s22, s70, s0
	s_addc_u32 s23, s71, 0
	s_lshl_b32 s0, s7, 2
	s_sub_i32 s42, s0, 64
	s_lshl_b32 s0, s7, 7
	v_mul_f32_e32 v149, 0x3fb8aa3b, v48
	s_mov_b32 s39, 31
	s_mov_b32 s40, 2
	v_mul_f32_e32 v151, 0x41800000, v149
	s_waitcnt vmcnt(15)
	ds_write_b128 v184, v[0:3]
	s_waitcnt vmcnt(14)
	ds_write_b128 v185, v[4:7]
	s_waitcnt vmcnt(13)
	ds_write_b128 v184, v[8:11] offset:8704
	s_waitcnt vmcnt(12)
	ds_write_b128 v186, v[12:15]
	s_waitcnt vmcnt(11)
	ds_write_b128 v184, v[16:19] offset:17408
	s_waitcnt vmcnt(10)
	ds_write_b128 v187, v[20:23]
	s_waitcnt vmcnt(9)
	ds_write_b128 v184, v[24:27] offset:26112
	s_waitcnt vmcnt(8)
	ds_write_b128 v188, v[28:31]
	s_waitcnt vmcnt(7)
	ds_write_b128 v189, v[32:35]
	s_waitcnt vmcnt(6)
	ds_write_b128 v189, v[36:39] offset:8704
	s_waitcnt vmcnt(5)
	ds_write_b128 v190, v[40:43] offset:17408
	s_waitcnt vmcnt(4)
	ds_write_b128 v190, v[44:47] offset:26112
	v_or_b32_e32 v0, s9, v169
	s_waitcnt lgkmcnt(0)
	s_barrier
	v_mul_lo_u32 v0, v0, s3
	v_add_u32_e32 v1, s9, v180
	v_mov_b32_e32 v40, v145
	v_mov_b32_e32 v41, v145
	v_mov_b32_e32 v42, v145
	v_mov_b32_e32 v43, v145
	v_subrev_u32_e32 v194, s0, v1
	v_add_u32_e32 v195, v177, v0
	v_mov_b64_e32 v[58:59], v[42:43]
	v_mov_b64_e32 v[66:67], v[42:43]
	v_mov_b64_e32 v[74:75], v[42:43]
	v_mov_b64_e32 v[82:83], v[42:43]
	v_mov_b64_e32 v[90:91], v[42:43]
	v_mov_b64_e32 v[98:99], v[42:43]
	v_mov_b64_e32 v[106:107], v[42:43]
	v_mov_b64_e32 v[114:115], v[42:43]
	v_mov_b64_e32 v[130:131], v[42:43]
	v_mov_b64_e32 v[0:1], v[40:41]
	v_mov_b64_e32 v[4:5], v[40:41]
	v_mov_b64_e32 v[8:9], v[40:41]
	v_mov_b64_e32 v[16:17], v[40:41]
	v_mov_b64_e32 v[28:29], v[40:41]
	v_mov_b64_e32 v[46:47], v[42:43]
	v_mov_b64_e32 v[50:51], v[42:43]
	v_mov_b64_e32 v[62:63], v[42:43]
	v_mov_b64_e32 v[70:71], v[42:43]
	v_mov_b64_e32 v[78:79], v[42:43]
	v_mov_b64_e32 v[86:87], v[42:43]
	v_mov_b64_e32 v[94:95], v[42:43]
	v_mov_b64_e32 v[102:103], v[42:43]
	v_mov_b64_e32 v[110:111], v[42:43]
	v_mov_b64_e32 v[122:123], v[42:43]
	v_mov_b64_e32 v[138:139], v[42:43]
	v_mov_b64_e32 v[54:55], v[42:43]
	v_mov_b64_e32 v[36:37], v[40:41]
	v_mov_b64_e32 v[32:33], v[40:41]
	v_mov_b64_e32 v[24:25], v[40:41]
	v_mov_b64_e32 v[20:21], v[40:41]
	v_mov_b64_e32 v[12:13], v[40:41]
	v_mul_f32_e32 v153, 0, v149
	v_add_f32_e32 v155, v149, v149
	v_mul_f32_e32 v157, 0x40400000, v149
	v_mul_f32_e32 v159, 0x41880000, v149
	v_mul_f32_e32 v161, 0x41900000, v149
	v_mul_f32_e32 v193, 0x41980000, v149
	v_mov_b32_e32 v164, v145
	v_mov_b32_e32 v165, v145
	v_mov_b32_e32 v166, 0xf149f2ca
	v_mov_b64_e32 v[56:57], v[40:41]
	v_mov_b64_e32 v[64:65], v[40:41]
	v_mov_b64_e32 v[72:73], v[40:41]
	v_mov_b64_e32 v[80:81], v[40:41]
	v_mov_b64_e32 v[88:89], v[40:41]
	v_mov_b64_e32 v[96:97], v[40:41]
	v_mov_b64_e32 v[104:105], v[40:41]
	v_mov_b64_e32 v[112:113], v[40:41]
	v_mov_b64_e32 v[128:129], v[40:41]
	v_mov_b64_e32 v[2:3], v[42:43]
	v_mov_b64_e32 v[6:7], v[42:43]
	v_mov_b64_e32 v[10:11], v[42:43]
	v_mov_b64_e32 v[18:19], v[42:43]
	v_mov_b64_e32 v[30:31], v[42:43]
	v_mov_b64_e32 v[44:45], v[40:41]
	v_mov_b64_e32 v[48:49], v[40:41]
	v_mov_b64_e32 v[60:61], v[40:41]
	v_mov_b64_e32 v[68:69], v[40:41]
	v_mov_b64_e32 v[76:77], v[40:41]
	v_mov_b64_e32 v[84:85], v[40:41]
	v_mov_b64_e32 v[92:93], v[40:41]
	v_mov_b64_e32 v[100:101], v[40:41]
	v_mov_b64_e32 v[108:109], v[40:41]
	v_mov_b64_e32 v[120:121], v[40:41]
	v_mov_b64_e32 v[136:137], v[40:41]
	v_mov_b32_e32 v167, 0xf149f2ca
	v_mov_b64_e32 v[52:53], v[40:41]
	v_mov_b64_e32 v[38:39], v[42:43]
	v_mov_b64_e32 v[34:35], v[42:43]
	v_mov_b64_e32 v[26:27], v[42:43]
	v_mov_b64_e32 v[22:23], v[42:43]
	v_mov_b64_e32 v[14:15], v[42:43]
	v_readfirstlane_b32 s5, v149
	v_readfirstlane_b32 s6, v155
	v_readfirstlane_b32 s7, v157
	v_readfirstlane_b32 s8, v151
	v_readfirstlane_b32 s9, v159
	v_readfirstlane_b32 s10, v161
	v_readfirstlane_b32 s11, v193
	s_mov_b32 s4, 0
	s_mov_b32 s12, 0x3e0293ee
	s_mov_b32 s13, 0x3e0293ee
	v_readfirstlane_b32 s86, v149
	v_readfirstlane_b32 s87, v151
	v_readfirstlane_b32 s88, v155
	v_readfirstlane_b32 s89, v157
	v_readfirstlane_b32 s90, v159
	ds_read_b128 v[240:243], v195
	ds_read_b128 v[244:247], v195 offset:64
	ds_read_b128 v[248:251], v195 offset:128
	ds_read_b128 v[252:255], v195 offset:192
	ds_read_b128 v[148:151], v195 offset:34816
	ds_read_b128 v[152:155], v195 offset:34880
	ds_read_b128 v[156:159], v195 offset:34944
	ds_read_b128 v[184:187], v195 offset:35008
	s_waitcnt lgkmcnt(0)

.Latt_top_done:
	s_sub_i32 s0, s39, 31
	s_cmp_gt_u32 s0, s41
	s_cbranch_scc1 .LBB0_235
	s_cmp_gt_u32 s39, s37
	s_cbranch_scc1 .Latt_diag
	v_add_u32_e32 v168, s43, v178
	ds_read_b128 v[196:199], v168
	ds_read_b128 v[200:203], v168 offset:4352
	ds_read_b128 v[214:217], v168 offset:64
	ds_read_b128 v[218:221], v168 offset:4416
	ds_read_b128 v[222:225], v168 offset:128
	ds_read_b128 v[226:229], v168 offset:4480
	ds_read_b128 v[234:237], v168 offset:192
	ds_read_b128 v[230:233], v168 offset:4544
	ds_read_b128 v[206:209], v168 offset:8704
	ds_read_b128 v[210:213], v168 offset:13056
	v_cvt_f32_i32_e32 v238, v194
	s_waitcnt lgkmcnt(9)
	v_mfma_f32_16x16x32_bf16 v[196:199], v[196:199], v[240:243], 0
	s_waitcnt lgkmcnt(8)
	v_mfma_f32_16x16x32_bf16 v[200:203], v[200:203], v[240:243], 0
	s_waitcnt lgkmcnt(7)
	v_mfma_f32_16x16x32_bf16 v[196:199], v[214:217], v[244:247], v[196:199]
	ds_read_b128 v[214:217], v168 offset:8768
	s_waitcnt lgkmcnt(7)
	v_mfma_f32_16x16x32_bf16 v[200:203], v[218:221], v[244:247], v[200:203]
	ds_read_b128 v[218:221], v168 offset:13120
	s_waitcnt lgkmcnt(7)
	v_mfma_f32_16x16x32_bf16 v[196:199], v[222:225], v[248:251], v[196:199]
	ds_read_b128 v[222:225], v168 offset:8832
	s_waitcnt lgkmcnt(7)
	v_mfma_f32_16x16x32_bf16 v[200:203], v[226:229], v[248:251], v[200:203]
	ds_read_b128 v[226:229], v168 offset:13184
	s_waitcnt lgkmcnt(7)
	v_mfma_f32_16x16x32_bf16 v[234:237], v[234:237], v[252:255], v[196:199]
	s_waitcnt lgkmcnt(6)
	v_mfma_f32_16x16x32_bf16 v[202:205], v[230:233], v[252:255], v[200:203]
	ds_read_b128 v[230:233], v168 offset:13248
	v_mul_f32_e64 v238, -s86, v238
	s_nop 3
	v_pk_fma_f32 v[198:199], v[234:235], s[12:13], v[238:239] op_sel_hi:[1,0,0]
	v_pk_fma_f32 v[200:201], v[236:237], s[12:13], v[238:239] op_sel_hi:[1,0,0]
	s_waitcnt lgkmcnt(6)
	v_mfma_f32_16x16x32_bf16 v[206:209], v[206:209], v[148:151], 0
	v_pk_add_f32 v[198:199], v[198:199], s[4:5]
	s_waitcnt lgkmcnt(5)
	v_mfma_f32_16x16x32_bf16 v[210:213], v[210:213], v[148:151], 0
	v_pk_add_f32 v[200:201], v[200:201], s[6:7]
	s_waitcnt lgkmcnt(4)
	v_mfma_f32_16x16x32_bf16 v[206:209], v[214:217], v[152:155], v[206:209]
	ds_read_b128 v[214:217], v168 offset:8896
	v_pk_fma_f32 v[202:203], v[202:203], s[12:13], v[238:239] op_sel_hi:[1,0,0]
	v_pk_fma_f32 v[204:205], v[204:205], s[12:13], v[238:239] op_sel_hi:[1,0,0]
	v_max3_f32 v196, v198, s33, v199
	v_pk_add_f32 v[202:203], v[202:203], s[8:9]
	v_pk_add_f32 v[204:205], v[204:205], s[10:11]
	v_max3_f32 v196, v196, v200, v201
	s_waitcnt lgkmcnt(4)
	v_mfma_f32_16x16x32_bf16 v[210:213], v[218:221], v[152:155], v[210:213]
	v_max3_f32 v196, v196, v202, v203
	s_waitcnt lgkmcnt(3)
	v_mfma_f32_16x16x32_bf16 v[206:209], v[222:225], v[156:159], v[206:209]
	v_max3_f32 v196, v196, v204, v205
	v_mov_b32_e32 v234, v196
	s_nop 1
	v_permlane16_swap_b32_e32 v196, v234
	v_max_f32_e32 v234, v234, v234
	v_max_f32_e32 v196, v196, v196
	s_waitcnt lgkmcnt(2)
	v_mfma_f32_16x16x32_bf16 v[210:213], v[226:229], v[156:159], v[210:213]
	v_max_f32_e32 v196, v196, v234
	v_mov_b32_e32 v168, v196
	s_nop 1
	v_permlane32_swap_b32_e32 v196, v168
	s_waitcnt lgkmcnt(0)
	v_mfma_f32_16x16x32_bf16 v[206:209], v[214:217], v[184:187], v[206:209]
	v_max3_f32 v196, v167, v196, v168
	v_sub_f32_e32 v167, v167, v196
	v_exp_f32_e32 v167, v167
	v_mfma_f32_16x16x32_bf16 v[210:213], v[230:233], v[184:187], v[210:213]
	s_nop 3
	v_pk_fma_f32 v[206:207], v[206:207], s[12:13], v[238:239] op_sel_hi:[1,0,0]
	v_pk_fma_f32 v[208:209], v[208:209], s[12:13], v[238:239] op_sel_hi:[1,0,0]
	s_nop 1
	v_pk_fma_f32 v[210:211], v[210:211], s[12:13], v[238:239] op_sel_hi:[1,0,0]
	v_pk_fma_f32 v[212:213], v[212:213], s[12:13], v[238:239] op_sel_hi:[1,0,0]
	v_pk_add_f32 v[206:207], v[206:207], s[4:5]
	v_pk_add_f32 v[208:209], v[208:209], s[6:7]
	v_pk_add_f32 v[210:211], v[210:211], s[8:9]
	v_pk_add_f32 v[212:213], v[212:213], s[10:11]
	v_max3_f32 v168, v206, s33, v207
	v_max3_f32 v168, v168, v208, v209
	v_max3_f32 v168, v168, v210, v211
	v_max3_f32 v168, v168, v212, v213
	v_mov_b32_e32 v197, v168
	s_nop 1
	v_permlane16_swap_b32_e32 v168, v197
	v_max_f32_e32 v197, v197, v197
	v_max_f32_e32 v168, v168, v168
	v_max_f32_e32 v168, v168, v197
	v_mov_b32_e32 v197, v168
	s_nop 1
	v_permlane32_swap_b32_e32 v168, v197
	v_max3_f32 v197, v166, v168, v197
	v_sub_f32_e32 v166, v166, v197
	v_exp_f32_e32 v166, v166
	s_branch .Latt_s1done

.LBB0_234:
	v_add_u32_e32 v238, s43, v179
	ds_read_b64_tr_b16 v[214:215], v238 offset:17408
	ds_read_b64_tr_b16 v[216:217], v238 offset:26112
	ds_read_b64_tr_b16 v[218:219], v238 offset:17440
	ds_read_b64_tr_b16 v[220:221], v238 offset:26144
	v_pk_add_f32 v[198:199], v[198:199], v[196:197] op_sel_hi:[1,0] neg_lo:[0,1] neg_hi:[0,1]
	v_pk_add_f32 v[200:201], v[200:201], v[196:197] op_sel_hi:[1,0] neg_lo:[0,1] neg_hi:[0,1]
	v_pk_add_f32 v[202:203], v[202:203], v[196:197] op_sel_hi:[1,0] neg_lo:[0,1] neg_hi:[0,1]
	v_pk_add_f32 v[204:205], v[204:205], v[196:197] op_sel_hi:[1,0] neg_lo:[0,1] neg_hi:[0,1]
	v_pk_add_f32 v[206:207], v[206:207], v[196:197] op_sel:[0,1] op_sel_hi:[1,1] neg_lo:[0,1] neg_hi:[0,1]
	v_pk_add_f32 v[208:209], v[208:209], v[196:197] op_sel:[0,1] op_sel_hi:[1,1] neg_lo:[0,1] neg_hi:[0,1]
	v_pk_add_f32 v[210:211], v[210:211], v[196:197] op_sel:[0,1] op_sel_hi:[1,1] neg_lo:[0,1] neg_hi:[0,1]
	v_pk_add_f32 v[212:213], v[212:213], v[196:197] op_sel:[0,1] op_sel_hi:[1,1] neg_lo:[0,1] neg_hi:[0,1]
	v_exp_f32_e32 v231, v202
	v_exp_f32_e32 v233, v203
	v_exp_f32_e32 v235, v204
	v_exp_f32_e32 v237, v205
	v_exp_f32_e32 v230, v210
	v_exp_f32_e32 v232, v211
	v_exp_f32_e32 v234, v212
	v_exp_f32_e32 v236, v213
	ds_read_b64_tr_b16 v[202:203], v238 offset:17472
	ds_read_b64_tr_b16 v[204:205], v238 offset:26176
	ds_read_b64_tr_b16 v[210:211], v238 offset:17504
	ds_read_b64_tr_b16 v[212:213], v238 offset:26208
	v_exp_f32_e32 v223, v198
	v_exp_f32_e32 v225, v199
	v_exp_f32_e32 v227, v200
	v_exp_f32_e32 v229, v201
	v_exp_f32_e32 v222, v206
	v_exp_f32_e32 v224, v207
	v_exp_f32_e32 v226, v208
	v_exp_f32_e32 v228, v209
	v_cvt_pk_bf16_f32 v198, v223, v225
	v_cvt_pk_bf16_f32 v199, v227, v229
	v_cvt_pk_bf16_f32 v200, v231, v233
	v_cvt_pk_bf16_f32 v201, v235, v237
	v_cvt_pk_bf16_f32 v206, v222, v224
	v_cvt_pk_bf16_f32 v207, v226, v228
	v_cvt_pk_bf16_f32 v208, v230, v232
	v_cvt_pk_bf16_f32 v209, v234, v236
	v_pk_add_f32 v[222:223], v[224:225], v[222:223]
	v_pk_add_f32 v[222:223], v[226:227], v[222:223]
	v_pk_add_f32 v[222:223], v[228:229], v[222:223]
	v_pk_add_f32 v[222:223], v[230:231], v[222:223]
	v_pk_add_f32 v[222:223], v[232:233], v[222:223]
	v_pk_add_f32 v[222:223], v[234:235], v[222:223]
	v_pk_add_f32 v[222:223], v[236:237], v[222:223]
	ds_read_b64_tr_b16 v[224:225], v238 offset:17536
	ds_read_b64_tr_b16 v[226:227], v238 offset:26240
	ds_read_b64_tr_b16 v[228:229], v238 offset:17568
	ds_read_b64_tr_b16 v[230:231], v238 offset:26272
	ds_read_b64_tr_b16 v[232:233], v238 offset:17600
	ds_read_b64_tr_b16 v[234:235], v238 offset:26304
	s_waitcnt lgkmcnt(12)
	v_mfma_f32_16x16x32_bf16 v[136:139], v[214:217], v[198:201], v[136:139]
	v_mfma_f32_16x16x32_bf16 v[128:131], v[214:217], v[206:209], v[128:131]
	ds_read_b64_tr_b16 v[214:215], v238 offset:17632
	ds_read_b64_tr_b16 v[216:217], v238 offset:26336
	s_waitcnt lgkmcnt(12)
	v_mfma_f32_16x16x32_bf16 v[120:123], v[218:221], v[198:201], v[120:123]
	v_mfma_f32_16x16x32_bf16 v[112:115], v[218:221], v[206:209], v[112:115]
	ds_read_b64_tr_b16 v[218:219], v238 offset:17664
	ds_read_b64_tr_b16 v[220:221], v238 offset:26368
	v_fma_f32 v164, v164, v166, v222
	v_fma_f32 v165, v165, v167, v223
	s_waitcnt lgkmcnt(12)
	v_mfma_f32_16x16x32_bf16 v[108:111], v[202:205], v[198:201], v[108:111]
	v_mfma_f32_16x16x32_bf16 v[104:107], v[202:205], v[206:209], v[104:107]
	ds_read_b64_tr_b16 v[202:203], v238 offset:17696
	ds_read_b64_tr_b16 v[204:205], v238 offset:26400
	s_waitcnt lgkmcnt(12)
	v_mfma_f32_16x16x32_bf16 v[100:103], v[210:213], v[198:201], v[100:103]
	v_mfma_f32_16x16x32_bf16 v[96:99], v[210:213], v[206:209], v[96:99]
	ds_read_b64_tr_b16 v[210:211], v238 offset:17728
	ds_read_b64_tr_b16 v[212:213], v238 offset:26432
	s_waitcnt lgkmcnt(12)
	v_mfma_f32_16x16x32_bf16 v[92:95], v[224:227], v[198:201], v[92:95]
	v_mfma_f32_16x16x32_bf16 v[88:91], v[224:227], v[206:209], v[88:91]
	ds_read_b64_tr_b16 v[224:225], v238 offset:17760
	ds_read_b64_tr_b16 v[226:227], v238 offset:26464
	s_waitcnt lgkmcnt(12)
	v_mfma_f32_16x16x32_bf16 v[84:87], v[228:231], v[198:201], v[84:87]
	v_mfma_f32_16x16x32_bf16 v[80:83], v[228:231], v[206:209], v[80:83]
	ds_read_b64_tr_b16 v[228:229], v238 offset:17792
	ds_read_b64_tr_b16 v[230:231], v238 offset:26496
	s_waitcnt lgkmcnt(12)
	v_mfma_f32_16x16x32_bf16 v[76:79], v[232:235], v[198:201], v[76:79]
	v_mfma_f32_16x16x32_bf16 v[72:75], v[232:235], v[206:209], v[72:75]
	ds_read_b64_tr_b16 v[232:233], v238 offset:17824
	ds_read_b64_tr_b16 v[234:235], v238 offset:26528
	s_waitcnt lgkmcnt(12)
	v_mfma_f32_16x16x32_bf16 v[68:71], v[214:217], v[198:201], v[68:71]
	v_mfma_f32_16x16x32_bf16 v[64:67], v[214:217], v[206:209], v[64:67]
	ds_read_b64_tr_b16 v[214:215], v238 offset:17856
	ds_read_b64_tr_b16 v[216:217], v238 offset:26560
	s_waitcnt lgkmcnt(12)
	v_mfma_f32_16x16x32_bf16 v[60:63], v[218:221], v[198:201], v[60:63]
	v_mfma_f32_16x16x32_bf16 v[56:59], v[218:221], v[206:209], v[56:59]
	ds_read_b64_tr_b16 v[218:219], v238 offset:17888
	ds_read_b64_tr_b16 v[220:221], v238 offset:26592
	s_waitcnt lgkmcnt(12)
	v_mfma_f32_16x16x32_bf16 v[48:51], v[202:205], v[198:201], v[48:51]
	v_mfma_f32_16x16x32_bf16 v[40:43], v[202:205], v[206:209], v[40:43]
	s_waitcnt lgkmcnt(10)
	v_mfma_f32_16x16x32_bf16 v[44:47], v[210:213], v[198:201], v[44:47]
	v_mfma_f32_16x16x32_bf16 v[52:55], v[210:213], v[206:209], v[52:55]
	s_waitcnt lgkmcnt(8)
	v_mfma_f32_16x16x32_bf16 v[28:31], v[224:227], v[198:201], v[28:31]
	v_mfma_f32_16x16x32_bf16 v[36:39], v[224:227], v[206:209], v[36:39]
	s_waitcnt lgkmcnt(6)
	v_mfma_f32_16x16x32_bf16 v[16:19], v[228:231], v[198:201], v[16:19]
	v_mfma_f32_16x16x32_bf16 v[32:35], v[228:231], v[206:209], v[32:35]
	s_waitcnt lgkmcnt(4)
	v_mfma_f32_16x16x32_bf16 v[8:11], v[232:235], v[198:201], v[8:11]
	v_mfma_f32_16x16x32_bf16 v[24:27], v[232:235], v[206:209], v[24:27]
	s_waitcnt lgkmcnt(2)
	v_mfma_f32_16x16x32_bf16 v[4:7], v[214:217], v[198:201], v[4:7]
	v_mfma_f32_16x16x32_bf16 v[20:23], v[214:217], v[206:209], v[20:23]
	s_waitcnt lgkmcnt(0)
	v_mfma_f32_16x16x32_bf16 v[0:3], v[218:221], v[198:201], v[0:3]
	v_mfma_f32_16x16x32_bf16 v[12:15], v[218:221], v[206:209], v[12:15]
	s_add_i32 s0, s40, -1
	s_cmp_ge_u32 s0, s38
	s_cbranch_scc0 .LBB0_236
	s_branch .LBB0_238
